# scan V-transpose staging: token pairs packed with v_permlane16_swap, 4 dword LDS stores instead of 16 halfword stores per staging wave
# speedup vs baseline: 1.0110x; 1.0010x over previous
; __device__ __forceinline__ int opaque_tid() { int t = threadIdx.x; asm volatile("" : "+v"(t)); return t; }
; #define LAS __attribute__((address_space(3)))
; __device__ __forceinline__ void scan_phase(LAS unsigned char* lds, bf16* proj, int G, int bid) {
;     const int tid = opaque_tid(), lane = tid & 63, wave = tid >> 6, fr = lane & 15, fq = lane >> 4;
;     constexpr int KRS = 132;
;     constexpr int SET = 34304, O_KR = 0, O_QR = 8448, O_QE = 16896, O_KE = 21248, O_KD = 25600, O_DV = 33792, O_VT = 2 * SET, QST = 272;
;     const int st = tid >> 4, sc8 = tid & 15;
;     const int pdk = tid >> 2, ptq = tid & 3;
;     const bool stager = tid < 256;
.LBB0_413:
	s_or_b64 exec, exec, s[0:1]
	v_readlane_b32 s0, v255, 33
	v_readlane_b32 s1, v255, 34
	s_xor_b64 s[0:1], s[0:1], -1
	v_writelane_b32 v255, s0, 46
	s_waitcnt lgkmcnt(0)
	s_barrier
	v_writelane_b32 v255, s1, 47
	s_nop 0
	v_readlane_b32 s0, v255, 39
	v_readlane_b32 s1, v255, 40
	s_and_b64 vcc, exec, s[0:1]
	s_mov_b64 s[0:1], -1
	s_cbranch_vccnz .LBB0_592
	v_readlane_b32 s4, v254, 43
	v_readlane_b32 s5, v254, 44
	s_and_b64 vcc, exec, s[4:5]
	s_cbranch_vccz .LBB0_496
	v_readlane_b32 s0, v253, 62
	v_readlane_b32 s1, v253, 63
	s_mov_b64 s[24:25], s[42:43]
	v_mov_b32_e32 v0, v209
	s_andn2_b64 vcc, exec, s[0:1]
	s_cbranch_vccnz .LBB0_444
	s_movk_i32 s0, 0x100
	v_ashrrev_i32_e32 v71, 2, v0
	v_cmp_gt_i32_e64 s[38:39], s0, v0
	s_movk_i32 s0, 0x200
	v_ashrrev_i32_e32 v70, 4, v0
	v_lshlrev_b32_e32 v72, 1, v71
	v_cmp_gt_i32_e64 s[42:43], s0, v0
	s_movk_i32 s0, 0x84
	v_and_b32_e32 v53, 15, v0
	v_add_u32_e32 v1, 0, v72
	s_waitcnt vmcnt(2)
	v_mul_lo_u32 v6, v70, s0
	v_add_u32_e32 v4, v1, v72
	v_bfe_u32 v5, v0, 4, 2
	v_lshlrev_b32_e32 v75, 2, v6
	v_lshlrev_b32_e32 v6, 5, v53
	s_waitcnt vmcnt(0)
	v_ashrrev_i32_e32 v8, 3, v0
	v_add3_u32 v76, 0, v75, v6
	v_lshlrev_b32_e32 v6, 9, v53
	v_readlane_b32 s4, v254, 11
	v_lshlrev_b32_e32 v8, 1, v8
	v_lshlrev_b32_e32 v9, 1, v70
	v_mad_u64_u32 v[54:55], s[0:1], v71, 60, v[4:5]
	v_and_b32_e32 v3, 3, v0
	v_add_u32_e32 v7, s4, v6
	v_and_b32_e32 v8, -16, v8
	v_and_b32_e32 v9, 6, v9
	s_movk_i32 s0, 0xffc4
	v_add3_u32 v77, v7, v8, v9
	v_mul_u32_u24_e32 v80, 0x210, v3
	v_mul_u32_u24_e32 v7, 0x220, v3
	v_mul_lo_u32 v84, v71, s0
	v_readlane_b32 s0, v254, 12
	v_lshl_add_u32 v81, v80, 2, v4
	v_lshl_add_u32 v82, v7, 1, v1
	v_and_b32_e32 v206, 12, v71
	v_lshlrev_b32_e32 v206, 1, v206
	v_bfe_u32 v207, v71, 4, 1
	v_lshl_or_b32 v206, v207, 2, v206
	v_and_b32_e32 v207, 3, v71
	v_or_b32_e32 v206, v206, v207
	v_and_b32_e32 v207, 0xffffffe0, v71
	v_or_b32_e32 v206, v206, v207
	v_lshlrev_b32_e32 v206, 1, v206
	v_sub_u32_e32 v82, v82, v72
	v_add_u32_e32 v82, v82, v206
	v_add_u32_e32 v1, s0, v6
	v_and_b32_e32 v4, -16, v71
	v_add3_u32 v85, v1, v8, v9
	v_and_b32_e32 v204, 3, v53
	v_lshlrev_b32_e32 v204, 4, v204
	v_xor_b32_e32 v77, v77, v204
	v_xor_b32_e32 v85, v85, v204
	v_bfe_u32 v204, v53, 2, 1
	v_lshlrev_b32_e32 v204, 6, v204
	v_sub_u32_e32 v180, v77, v204
	v_sub_u32_e32 v181, v85, v204
	v_add_u32_e32 v77, v77, v204
	v_add_u32_e32 v85, v85, v204
	v_lshlrev_b32_e32 v89, 4, v5
	v_lshlrev_b32_e32 v56, 3, v5
	v_lshlrev_b32_e32 v1, 2, v5
	v_ashrrev_i32_e32 v5, 31, v4
	v_lshl_add_u64 v[4:5], v[4:5], 1, s[82:83]
	v_mov_b32_e32 v57, v2
	v_lshlrev_b32_e32 v83, 6, v71
	v_lshl_add_u64 v[58:59], v[4:5], 0, v[56:57]
	v_lshlrev_b32_e32 v4, 4, v53
	v_mov_b32_e32 v5, v2
	s_movk_i32 s0, 0x10ff
	v_cmp_lt_i32_e64 s[40:41], s22, v0
	v_lshlrev_b32_e32 v73, 4, v0
	v_lshl_add_u64 v[60:61], s[82:83], 0, v[4:5]
	v_lshlrev_b32_e32 v57, 6, v53
	v_cmp_gt_u32_e64 s[48:49], v1, v53
	v_cmp_lt_u32_e64 s[50:51], v1, v53
	v_or_b32_e32 v4, 2, v1
	v_or_b32_e32 v1, 3, v1
	v_bitop3_b32 v92, v0, s0, 15 bitop3:0x6c
	v_and_b32_e32 v0, 0xfffffc00, v83
	v_cmp_gt_u32_e64 s[54:55], v1, v53
	v_lshlrev_b32_e32 v1, 10, v3
	v_or3_b32 v0, v0, v57, v89
	v_sub_u32_e32 v74, 0xff, v70
	v_lshlrev_b32_e32 v52, 3, v53
	v_add_u32_e32 v78, 16, v70
	v_sub_u32_e32 v79, 0xef, v70
	v_cmp_eq_u32_e64 s[44:45], 0, v3
	v_cmp_lt_u32_e64 s[46:47], 1, v3
	v_lshlrev_b32_e32 v55, 4, v3
	v_bfe_u32 v208, v209, 4, 2
	v_sub_u32_e32 v208, 0, v208
	v_and_b32_e32 v208, 3, v208
	v_lshlrev_b32_e32 v208, 4, v208
	v_xor_b32_e32 v55, v55, v208
	v_bfe_u32 v210, v209, 2, 2
	v_sub_u32_e32 v210, 0, v210
	v_and_b32_e32 v210, 3, v210
	v_bfe_u32 v212, v209, 4, 2
	v_xor_b32_e32 v210, v210, v212
	v_sub_u32_e32 v210, v210, v212
	v_lshlrev_b32_e32 v210, 4, v210
	v_add_u32_e32 v210, v210, v57
	v_add_u32_e32 v86, 32, v70
	v_sub_u32_e32 v87, 0xdf, v70
	v_mul_u32_u24_e32 v88, 0x110, v53
	v_cmp_gt_u32_e64 s[52:53], v4, v53
	v_sub_u32_e32 v90, 0, v1
	v_sub_u32_e32 v91, 0, v70
	v_lshrrev_b32_e32 v204, 5, v0
	v_and_b32_e32 v204, 0x70, v204
	v_xor_b32_e32 v0, v0, v204
	v_add_u32_e32 v93, s4, v0
	v_and_b32_e32 v243, 15, v209
	v_lshlrev_b32_e32 v244, 9, v243
	v_bfe_u32 v245, v209, 4, 2
	v_bfe_u32 v246, v243, 2, 1
	v_xor_b32_e32 v246, v246, v245
	v_and_b32_e32 v246, 1, v246
	v_lshl_add_u32 v244, v246, 6, v244
	v_lshrrev_b32_e32 v246, 6, v209
	v_xor_b32_e32 v246, v246, v243
	v_and_b32_e32 v246, 3, v246
	v_lshl_add_u32 v244, v246, 4, v244
	v_lshrrev_b32_e32 v246, 1, v245
	v_lshl_add_u32 v244, v246, 2, v244
	v_add_u32_e32 v236, s4, v244
	v_and_b32_e32 v246, 1, v245
	v_mov_b32_e32 v237, 0x5040100
	v_mov_b32_e32 v247, 0x7060302
	v_cmp_eq_u32_e32 vcc, 1, v246
	s_nop 1
	v_cndmask_b32_e32 v237, v237, v247, vcc
	s_mov_b32 s13, s2
	s_branch .LBB0_418

; #define SC_LOAD(c_) do { const bf16* rp_ = proj + (size_t)scan_row16(b, dir, (c_), st) * HIN + h * 128 + sc8 * 8; \
;         rq = *(const u32x4*)rp_; rk = *(const u32x4*)(rp_ + kcol - h * 128); rv = *(const u32x4*)(rp_ + 3072); } while (0)
; __device__ __forceinline__ void scan_phase(LAS unsigned char* lds, bf16* proj, int G, int bid) {
;     ...
;         if (stager) SC_LOAD(0);
;         __syncthreads();
;         if (stager) { SC_WRITE(0); SC_LOAD(1); }
.LBB0_423:
	s_or_b64 exec, exec, s[4:5]
	s_waitcnt lgkmcnt(0)
	s_barrier
	s_and_saveexec_b64 s[4:5], s[38:39]
	s_cbranch_execz .LBB0_425
	s_cmp_eq_u32 s15, 0
	s_cselect_b64 vcc, -1, 0
	s_lshl_b32 s6, s14, 8
	s_add_i32 s6, s6, 0x10000
	v_cndmask_b32_e32 v0, v79, v78, vcc
	v_add_u32_e32 v3, s6, v0
	v_mov_b64_e32 v[0:1], s[82:83]
	v_mad_i64_i32 v[0:1], s[6:7], v3, s3, v[0:1]
	s_lshl_b32 s6, s0, 1
	s_mov_b32 s7, s72
	v_lshl_add_u64 v[0:1], v[0:1], 0, s[6:7]
	v_mov_b32_e32 v17, v2
	s_add_i32 s7, s1, s0
	s_waitcnt vmcnt(1)
	v_lshlrev_b32_e32 v18, 16, v12
	v_and_b32_e32 v19, 0xffff0000, v12
	v_lshlrev_b32_e32 v22, 16, v4
	v_and_b32_e32 v23, 0xffff0000, v4
	v_lshlrev_b32_e32 v20, 16, v13
	v_and_b32_e32 v21, 0xffff0000, v13
	v_lshlrev_b32_e32 v24, 16, v5
	v_and_b32_e32 v25, 0xffff0000, v5
	v_lshl_add_u64 v[0:1], v[0:1], 0, v[16:17]
	s_lshl_b32 s16, s7, 1
	s_mov_b32 s17, s72
	s_waitcnt vmcnt(0)
	v_mov_b32_e32 v238, v8
	v_mov_b32_e32 v239, v9
	v_mov_b32_e32 v240, v10
	v_mov_b32_e32 v241, v11
	s_nop 1
	v_permlane16_swap_b32_e32 v8, v238
	v_permlane16_swap_b32_e32 v9, v239
	v_permlane16_swap_b32_e32 v10, v240
	v_permlane16_swap_b32_e32 v11, v241
	v_perm_b32 v238, v238, v8, v237
	v_perm_b32 v239, v239, v9, v237
	v_perm_b32 v240, v240, v10, v237
	v_perm_b32 v241, v241, v11, v237
	ds_write_b32 v236, v238 offset:0
	ds_write_b32 v236, v239 offset:128
	ds_write_b32 v236, v240 offset:256
	ds_write_b32 v236, v241 offset:384
	ds_write_b128 v76, v[18:21]
	ds_write_b128 v76, v[22:25] offset:8448
	v_lshl_add_u64 v[8:9], v[0:1], 0, s[16:17]
	v_lshlrev_b32_e32 v12, 16, v14
	v_and_b32_e32 v13, 0xffff0000, v14
	v_lshlrev_b32_e32 v4, 16, v6
	v_and_b32_e32 v5, 0xffff0000, v6
	v_lshlrev_b32_e32 v14, 16, v15
	v_and_b32_e32 v15, 0xffff0000, v15
	v_lshlrev_b32_e32 v6, 16, v7
	v_and_b32_e32 v7, 0xffff0000, v7
	v_subrev_co_u32_e32 v8, vcc, s6, v8
	ds_write_b128 v76, v[12:15] offset:16
	ds_write_b128 v76, v[4:7] offset:8464
	v_subbrev_co_u32_e32 v9, vcc, 0, v9, vcc
	global_load_dwordx4 v[4:7], v[0:1], off
	global_load_dwordx4 v[12:15], v[8:9], off offset:2048
	v_add_co_u32_e32 v0, vcc, 0x1000, v0
	s_nop 1
	v_addc_co_u32_e32 v1, vcc, 0, v1, vcc
	global_load_dwordx4 v[8:11], v[0:1], off offset:2048
; #define SC_LOAD(c_) do { const bf16* rp_ = proj + (size_t)scan_row16(b, dir, (c_), st) * HIN + h * 128 + sc8 * 8; \
;         rq = *(const u32x4*)rp_; rk = *(const u32x4*)(rp_ + kcol - h * 128); rv = *(const u32x4*)(rp_ + 3072); } while (0)
; __device__ __forceinline__ void scan_phase(LAS unsigned char* lds, bf16* proj, int G, int bid) {
;     ...
;         SC_PREP(0);
;         if (stager) { SC_WRITE(1); SC_LOAD(2); }
.LBB0_425:
	s_or_b64 exec, exec, s[4:5]
	s_waitcnt lgkmcnt(0)
	s_barrier
	ds_read2_b32 v[18:19], v81 offset1:132
	v_add_u32_e32 v0, 0x2000, v81
	ds_read2_b32 v[20:21], v0 offset0:64 offset1:196
	v_add_u32_e32 v0, 0x400, v81
	ds_read2_b32 v[22:23], v0 offset0:8 offset1:140
	v_add_u32_e32 v0, 0x2400, v81
	ds_read2_b32 v[24:25], v0 offset0:72 offset1:204
	s_waitcnt lgkmcnt(3)
	v_sub_f32_e32 v0, 1.0, v18
	v_max_f32_e32 v1, 0x3bdb8bac, v0
	v_sub_f32_e32 v0, 1.0, v19
	v_max_f32_e32 v0, 0x3bdb8bac, v0
	v_mul_f32_e32 v3, v1, v0
	s_waitcnt lgkmcnt(1)
	v_sub_f32_e32 v0, 1.0, v22
	v_max_f32_e32 v0, 0x3bdb8bac, v0
	v_mul_f32_e32 v17, v3, v0
	v_sub_f32_e32 v0, 1.0, v23
	v_max_f32_e32 v0, 0x3bdb8bac, v0
	v_mul_f32_e32 v28, v17, v0
	s_nop 1
	v_mul_f32_dpp v0, v28, v28 quad_perm:[0,0,1,2] row_mask:0xf bank_mask:0xf bound_ctrl:1
	v_cndmask_b32_e64 v0, v0, v28, s[44:45]
	s_nop 1
	v_mul_f32_dpp v26, v0, v0 quad_perm:[0,0,0,1] row_mask:0xf bank_mask:0xf bound_ctrl:1
	v_cndmask_b32_e64 v26, v0, v26, s[46:47]
	v_mov_b32_e32 v0, v2
	s_nop 1
	v_mov_b32_dpp v0, v26 quad_perm:[0,0,1,2] row_mask:0xf bank_mask:0xf
	v_cndmask_b32_e64 v29, v0, 1.0, s[44:45]
	v_mov_b32_e32 v0, v2
	v_mul_f32_e32 v1, v1, v29
	s_nop 0
	v_mov_b32_dpp v0, v26 quad_perm:[3,3,3,3] row_mask:0xf bank_mask:0xf
	v_rcp_f32_e32 v26, v1
	v_mul_f32_e32 v1, v20, v1
	v_cvt_pk_bf16_f32 v1, v1, s0
	ds_write_b16 v82, v1 offset:16896
	v_mul_f32_e32 v1, v3, v29
	v_rcp_f32_e32 v27, v1
	v_mul_f32_e32 v1, v21, v1
	v_cvt_pk_bf16_f32 v1, v1, s0
	ds_write_b16 v82, v1 offset:17168
	v_mul_f32_e32 v1, v17, v29
	v_rcp_f32_e32 v20, v1
	s_waitcnt lgkmcnt(2)
	v_mul_f32_e32 v1, v24, v1
	v_cvt_pk_bf16_f32 v1, v1, s0
	ds_write_b16 v82, v1 offset:17440
	v_mul_f32_e32 v1, v28, v29
	v_rcp_f32_e32 v21, v1
	v_mul_f32_e32 v1, v25, v1
	v_cvt_pk_bf16_f32 v1, v1, s0
	v_pk_mul_f32 v[18:19], v[18:19], v[26:27]
	ds_write_b16 v82, v1 offset:17712
	v_cvt_pk_bf16_f32 v1, v18, s0
	ds_write_b16 v82, v1 offset:21248
	v_pk_mul_f32 v[24:25], v[18:19], v[0:1] op_sel_hi:[1,0]
	v_cvt_pk_bf16_f32 v1, v19, s0
	v_pk_mul_f32 v[20:21], v[22:23], v[20:21]
	ds_write_b16 v82, v1 offset:21520
	v_cvt_pk_bf16_f32 v1, v20, s0
	ds_write_b16 v82, v1 offset:21792
	v_pk_mul_f32 v[22:23], v[20:21], v[0:1] op_sel_hi:[1,0]
	v_cvt_pk_bf16_f32 v1, v21, s0
	v_cvt_pk_bf16_f32 v18, v24, v25
	ds_write_b16 v82, v1 offset:22064
	v_cvt_pk_bf16_f32 v19, v22, v23
	v_add_u32_e32 v1, v54, v55
	ds_write_b64 v1, v[18:19] offset:25600
	s_and_saveexec_b64 s[4:5], s[44:45]
	v_readlane_b32 s74, v254, 33
	v_readlane_b32 s75, v254, 34
	v_add_u32_e32 v1, v54, v84
	ds_write_b32 v1, v0 offset:33792
	s_or_b64 exec, exec, s[4:5]
	s_add_i32 s16, s1, s0
	s_add_i32 s4, s16, 0x400
	s_mov_b32 s1, s72
	s_mov_b32 s5, s72
	v_mov_b64_e32 v[18:19], s[4:5]
	v_mov_b64_e32 v[0:1], s[0:1]
	s_and_saveexec_b64 s[18:19], s[40:41]
	s_xor_b64 s[34:35], exec, s[18:19]
	s_lshl_b32 s6, s14, 8
	s_add_i32 s17, s6, 0x10000
	s_sub_u32 s6, 0, s0
	s_subb_u32 s7, 0, 0
	v_mov_b64_e32 v[18:19], s[4:5]
	v_mov_b64_e32 v[0:1], s[0:1]
	s_or_saveexec_b64 s[4:5], s[34:35]
	v_mov_b64_e32 v[62:63], s[6:7]
	v_mov_b32_e32 v94, s17
	s_xor_b64 exec, exec, s[4:5]
	s_cbranch_execz .LBB0_431
	s_cmp_eq_u32 s15, 0
	s_cselect_b64 vcc, -1, 0
	s_lshl_b32 s1, s14, 8
	s_waitcnt vmcnt(1)
	v_lshlrev_b32_e32 v20, 16, v12
	v_and_b32_e32 v21, 0xffff0000, v12
	v_lshlrev_b32_e32 v24, 16, v4
	v_and_b32_e32 v25, 0xffff0000, v4
	v_lshlrev_b32_e32 v22, 16, v13
	v_and_b32_e32 v23, 0xffff0000, v13
	v_lshlrev_b32_e32 v26, 16, v5
	v_and_b32_e32 v27, 0xffff0000, v5
	v_lshlrev_b32_e32 v12, 16, v14
	v_and_b32_e32 v13, 0xffff0000, v14
	v_lshlrev_b32_e32 v4, 16, v6
	v_and_b32_e32 v5, 0xffff0000, v6
	v_lshlrev_b32_e32 v14, 16, v15
	v_and_b32_e32 v15, 0xffff0000, v15
	v_lshlrev_b32_e32 v6, 16, v7
	v_and_b32_e32 v7, 0xffff0000, v7
	s_add_i32 s18, s1, 0x10000
	v_cndmask_b32_e32 v1, v87, v86, vcc
	s_waitcnt vmcnt(0)
	v_mov_b32_e32 v238, v8
	v_mov_b32_e32 v239, v9
	v_mov_b32_e32 v240, v10
	v_mov_b32_e32 v241, v11
	s_nop 1
	v_permlane16_swap_b32_e32 v8, v238
	v_permlane16_swap_b32_e32 v9, v239
	v_permlane16_swap_b32_e32 v10, v240
	v_permlane16_swap_b32_e32 v11, v241
	v_perm_b32 v238, v238, v8, v237
	v_perm_b32 v239, v239, v9, v237
	v_perm_b32 v240, v240, v10, v237
	v_perm_b32 v241, v241, v11, v237
	ds_write_b32 v236, v238 offset:8192
	ds_write_b32 v236, v239 offset:8320
	ds_write_b32 v236, v240 offset:8448
	ds_write_b32 v236, v241 offset:8576
	ds_write_b128 v76, v[20:23] offset:34304
	ds_write_b128 v76, v[24:27] offset:42752
	ds_write_b128 v76, v[12:15] offset:34320
	ds_write_b128 v76, v[4:7] offset:42768
	v_add_u32_e32 v1, s18, v1
	v_mov_b64_e32 v[4:5], s[82:83]
	v_mad_i64_i32 v[4:5], s[6:7], v1, s3, v[4:5]
	s_lshl_b32 s6, s0, 1
	s_mov_b32 s7, s72
	v_lshl_add_u64 v[4:5], v[4:5], 0, s[6:7]
	v_mov_b32_e32 v17, v2
	v_lshl_add_u64 v[8:9], v[4:5], 0, v[16:17]
	s_lshl_b32 s16, s16, 1
	s_mov_b32 s17, s72
	v_lshl_add_u64 v[10:11], v[8:9], 0, s[16:17]
	v_subrev_co_u32_e32 v10, vcc, s6, v10
	global_load_dwordx4 v[4:7], v[8:9], off
	s_nop 0
	v_subbrev_co_u32_e32 v11, vcc, 0, v11, vcc
	global_load_dwordx4 v[12:15], v[10:11], off offset:2048
	v_add_co_u32_e32 v8, vcc, 0x1000, v8
	s_sub_u32 s0, 0, s0
	s_nop 0
	v_addc_co_u32_e32 v9, vcc, 0, v9, vcc
	global_load_dwordx4 v[8:11], v[8:9], off offset:2048
	s_subb_u32 s1, 0, 0
	v_mov_b64_e32 v[62:63], s[0:1]
	v_mov_b32_e32 v94, s18
	s_cmp_eq_u32 s15, 0
	s_cselect_b64 vcc, -1, 0
	v_add_u32_e32 v168, 16, v86
	v_add_u32_e32 v169, -16, v87
	v_cndmask_b32_e32 v1, v169, v168, vcc
	v_add_u32_e32 v1, s18, v1
	v_mov_b64_e32 v[168:169], s[82:83]
	s_nop 0
	v_mad_i64_i32 v[168:169], vcc, v1, s3, v[168:169]
	v_lshl_add_u64 v[168:169], v[168:169], 0, s[6:7]
	v_lshl_add_u64 v[172:173], v[168:169], 0, v[16:17]
	v_lshl_add_u64 v[174:175], v[172:173], 0, s[16:17]
	v_subrev_co_u32_e32 v174, vcc, s6, v174
	s_nop 1
	v_subbrev_co_u32_e32 v175, vcc, 0, v175, vcc
	global_load_dwordx4 v[168:171], v[172:173], off
	global_load_dwordx4 v[176:179], v[174:175], off offset:2048
	v_add_co_u32_e32 v172, vcc, 0x1000, v172
	s_nop 1
	v_addc_co_u32_e32 v173, vcc, 0, v173, vcc
	global_load_dwordx4 v[172:175], v[172:173], off offset:2048

; #define SC_LOAD(c_) do { const bf16* rp_ = proj + (size_t)scan_row16(b, dir, (c_), st) * HIN + h * 128 + sc8 * 8; \
;         rq = *(const u32x4*)rp_; rk = *(const u32x4*)(rp_ + kcol - h * 128); rv = *(const u32x4*)(rp_ + 3072); } while (0)
; __device__ __forceinline__ void scan_phase(LAS unsigned char* lds, bf16* proj, int G, int bid) {
;     ...
;                     u32x2 ow; ow.x = cvt_pk_bf16(oacc[0], oacc[1]); ow.y = cvt_pk_bf16(oacc[2], oacc[3]);
;                     *(u32x2*)(proj + (size_t)scan_row16(b, dir, c, fr) * HIN + kcol + wave * 16 + fq * 4) = ow;
;                 }
;             }
;             if (stager) { if (c + 2 < 272) SC_WRITE(c + 2); if (c + 3 < 272) SC_LOAD(c + 3); }
.LBB0_439:
	s_nop 0
	v_cvt_pk_bf16_f32 v48, v48, v49
	v_cvt_pk_bf16_f32 v49, v50, v51
	v_mad_i64_i32 v[0:1], s[0:1], v0, s3, v[66:67]
	global_store_dwordx2 v[0:1], v[48:49], off
	s_and_saveexec_b64 s[0:1], s[38:39]
	s_cbranch_execz .LBB0_432
	s_cmpk_gt_u32 s6, 0x10d
	s_cbranch_scc1 .LBB0_442
	v_lshlrev_b32_e32 v0, 2, v52
	v_add3_u32 v0, s14, v75, v0
	s_add_i32 s14, s6, 2
	s_and_b32 s15, s14, 0xffff
	s_mul_i32 s15, s15, 0xaaab
	s_lshr_b32 s15, s15, 17
	s_mul_i32 s15, s15, 3
	s_sub_i32 s14, s14, s15
	s_and_b32 s14, s14, 0xffff
	v_lshl_add_u32 v1, s14, 13, v77
	v_lshl_add_u32 v205, s14, 13, v180
	v_lshl_add_u32 v242, s14, 13, v236
	s_waitcnt vmcnt(4)
	v_lshlrev_b32_e32 v48, 16, v12
	v_and_b32_e32 v49, 0xffff0000, v12
	v_lshlrev_b32_e32 v98, 16, v4
	v_and_b32_e32 v99, 0xffff0000, v4
	v_lshlrev_b32_e32 v50, 16, v13
	v_and_b32_e32 v51, 0xffff0000, v13
	v_lshlrev_b32_e32 v100, 16, v5
	v_and_b32_e32 v101, 0xffff0000, v5
	v_mov_b32_e32 v238, v8
	v_mov_b32_e32 v239, v9
	v_mov_b32_e32 v240, v10
	v_mov_b32_e32 v241, v11
	s_nop 1
	v_permlane16_swap_b32_e32 v8, v238
	v_permlane16_swap_b32_e32 v9, v239
	v_permlane16_swap_b32_e32 v10, v240
	v_permlane16_swap_b32_e32 v11, v241
	v_perm_b32 v238, v238, v8, v237
	v_perm_b32 v239, v239, v9, v237
	v_perm_b32 v240, v240, v10, v237
	v_perm_b32 v241, v241, v11, v237
	ds_write_b32 v242, v238 offset:0
	ds_write_b32 v242, v239 offset:128
	ds_write_b32 v242, v240 offset:256
	ds_write_b32 v242, v241 offset:384
	ds_write_b128 v0, v[48:51]
	ds_write_b128 v0, v[98:101] offset:8448
	v_lshlrev_b32_e32 v48, 16, v14
	v_and_b32_e32 v49, 0xffff0000, v14
	v_lshlrev_b32_e32 v98, 16, v6
	v_and_b32_e32 v99, 0xffff0000, v6
	v_lshlrev_b32_e32 v50, 16, v15
	v_and_b32_e32 v51, 0xffff0000, v15
	v_lshlrev_b32_e32 v100, 16, v7
	v_and_b32_e32 v101, 0xffff0000, v7
	ds_write_b128 v0, v[48:51] offset:16
	ds_write_b128 v0, v[98:101] offset:8464

; #define SC_LOAD(c_) do { const bf16* rp_ = proj + (size_t)scan_row16(b, dir, (c_), st) * HIN + h * 128 + sc8 * 8; \
;         rq = *(const u32x4*)rp_; rk = *(const u32x4*)(rp_ + kcol - h * 128); rv = *(const u32x4*)(rp_ + 3072); } while (0)
; __device__ __forceinline__ void scan_phase(LAS unsigned char* lds, bf16* proj, int G, int bid) {
;     ...
;                     u32x2 ow; ow.x = cvt_pk_bf16(oacc[0], oacc[1]); ow.y = cvt_pk_bf16(oacc[2], oacc[3]);
;                     *(u32x2*)(proj + (size_t)scan_row16(b, dir, c, fr) * HIN + kcol + wave * 16 + fq * 4) = ow;
;                 }
;             }
;             if (stager) { if (c + 2 < 272) SC_WRITE(c + 2); if (c + 3 < 272) SC_LOAD(c + 3); }
.LscanB_439:
	s_nop 0
	v_cvt_pk_bf16_f32 v48, v48, v49
	v_cvt_pk_bf16_f32 v49, v50, v51
	v_mad_i64_i32 v[0:1], s[0:1], v0, s3, v[66:67]
	global_store_dwordx2 v[0:1], v[48:49], off
	s_and_saveexec_b64 s[0:1], s[38:39]
	s_cbranch_execz .LscanB_432
	s_cmpk_gt_u32 s6, 0x10d
	s_cbranch_scc1 .LscanB_442
	v_lshlrev_b32_e32 v0, 2, v52
	v_add3_u32 v0, s14, v75, v0
	s_add_i32 s14, s6, 2
	s_and_b32 s15, s14, 0xffff
	s_mul_i32 s15, s15, 0xaaab
	s_lshr_b32 s15, s15, 17
	s_mul_i32 s15, s15, 3
	s_sub_i32 s14, s14, s15
	s_and_b32 s14, s14, 0xffff
	v_lshl_add_u32 v1, s14, 13, v77
	v_lshl_add_u32 v205, s14, 13, v180
	v_lshl_add_u32 v242, s14, 13, v236
	s_cmpk_eq_u32 s6, 0x10d
	s_cbranch_scc1 .LscanB_wtail
	s_waitcnt vmcnt(4)
	s_branch .LscanB_wgo

.LscanB_wgo:
	v_lshlrev_b32_e32 v48, 16, v176
	v_and_b32_e32 v49, 0xffff0000, v176
	v_lshlrev_b32_e32 v98, 16, v168
	v_and_b32_e32 v99, 0xffff0000, v168
	v_lshlrev_b32_e32 v50, 16, v177
	v_and_b32_e32 v51, 0xffff0000, v177
	v_lshlrev_b32_e32 v100, 16, v169
	v_and_b32_e32 v101, 0xffff0000, v169
	v_mov_b32_e32 v238, v172
	v_mov_b32_e32 v239, v173
	v_mov_b32_e32 v240, v174
	v_mov_b32_e32 v241, v175
	s_nop 1
	v_permlane16_swap_b32_e32 v172, v238
	v_permlane16_swap_b32_e32 v173, v239
	v_permlane16_swap_b32_e32 v174, v240
	v_permlane16_swap_b32_e32 v175, v241
	v_perm_b32 v238, v238, v172, v237
	v_perm_b32 v239, v239, v173, v237
	v_perm_b32 v240, v240, v174, v237
	v_perm_b32 v241, v241, v175, v237
	ds_write_b32 v242, v238 offset:0
	ds_write_b32 v242, v239 offset:128
	ds_write_b32 v242, v240 offset:256
	ds_write_b32 v242, v241 offset:384
	ds_write_b128 v0, v[48:51]
	ds_write_b128 v0, v[98:101] offset:8448
	v_lshlrev_b32_e32 v48, 16, v178
	v_and_b32_e32 v49, 0xffff0000, v178
	v_lshlrev_b32_e32 v98, 16, v170
	v_and_b32_e32 v99, 0xffff0000, v170
	v_lshlrev_b32_e32 v50, 16, v179
	v_and_b32_e32 v51, 0xffff0000, v179
	v_lshlrev_b32_e32 v100, 16, v171
	v_and_b32_e32 v101, 0xffff0000, v171
	ds_write_b128 v0, v[48:51] offset:16
	ds_write_b128 v0, v[98:101] offset:8464
